# sample_gemm32 hand-written (LDS-DMA B, 44 A loads in flight) with per-workgroup K-chunk rotation to spread L2 channel load, on v43
# speedup vs baseline: 1.0080x; 1.0080x over previous
; #define LAS __attribute__((address_space(3)))
; #define SG_LA(c, d) do { _Pragma("unroll") for (int ks = 0; ks < 16; ++ks) d[ks] = *(const bf16x8*)(ap + (c) * CK + ks * 32); } while (0)
; #define SG_LB(c) do { _Pragma("unroll") for (int i = 0; i < 4; ++i) sb[i] = *(const u32x4*)(bp + (size_t)(8 * i) * DM + (c) * CK); } while (0)
; #define SG_SB(bufp) do { _Pragma("unroll") for (int i = 0; i < 4; ++i) *(LAS u32x4*)((bufp) + bw + (unsigned)(8 * i * BS * 2)) = sb[i]; } while (0)
; __device__ __forceinline__ void sample_gemm32(LAS unsigned char* lds, const bf16_t* A, const bf16_t* Bt, float* out, int ldo, int n0, int tid, int lane, int wave) {
;     constexpr int CK = 512, BS = CK + 8, BUFB = 32 * BS * 2, NC = DM / CK;
;     const int r = lane & 15, q8 = lane >> 4;
;     const bf16_t* ap = A + (size_t)(wave * 16 + r) * DM + q8 * 8;
;     const bf16_t* bp = Bt + (size_t)(tid >> 6) * DM + (tid & 63) * 8;
;     const unsigned bw = (unsigned)((tid >> 6) * BS + (tid & 63) * 8) * 2u;
;     f32x4 acc[2] = {{0.f, 0.f, 0.f, 0.f}, {0.f, 0.f, 0.f, 0.f}};
;     bf16x8 fa[16], fn[16]; u32x4 sb[4];
;     ...
;     SG_LB(0); SG_LA(0, fa);
;     SG_SB(lds);
;     SG_LB(1);
;     __syncthreads();
.LBB0_350:
	s_ashr_i32 s7, s6, 31
	s_lshl_b64 s[4:5], s[6:7], 17
	v_lshl_add_u64 v[178:179], v[164:165], 0, s[4:5]
	s_mul_i32 s10, s14, 0x410
	s_bfe_u32 s11, s6, 0x20003
	s_xor_b32 s4, s11, 0
	s_lshl_b32 s4, s4, 10
	s_mov_b32 s5, 0
	v_lshl_add_u64 v[240:241], v[166:167], 0, s[4:5]
	s_xor_b32 s4, s11, 1
	s_lshl_b32 s4, s4, 10
	s_mov_b32 s5, 0
	v_lshl_add_u64 v[242:243], v[166:167], 0, s[4:5]
	s_xor_b32 s4, s11, 2
	s_lshl_b32 s4, s4, 10
	s_mov_b32 s5, 0
	v_lshl_add_u64 v[248:249], v[166:167], 0, s[4:5]
	s_xor_b32 s4, s11, 3
	s_lshl_b32 s4, s4, 10
	s_mov_b32 s5, 0
	v_lshl_add_u64 v[250:251], v[166:167], 0, s[4:5]
	v_add_u32_e32 v238, 0x10400, v152
	v_mov_b32_e32 v228, 0
	v_mov_b32_e32 v229, 0
	v_mov_b32_e32 v230, 0
	v_mov_b32_e32 v231, 0
	v_mov_b32_e32 v232, 0
	v_mov_b32_e32 v233, 0
	v_mov_b32_e32 v234, 0
	v_mov_b32_e32 v235, 0
	s_xor_b32 s4, s11, 0
	s_lshl_b32 s4, s4, 10
	s_add_u32 s4, s4, 0x0
	s_mov_b32 s5, 0
	s_add_i32 m0, s10, 0x0
	v_lshl_add_u64 v[236:237], v[178:179], 0, s[4:5]
	global_load_lds_dwordx4 v[236:237], off
	s_xor_b32 s4, s11, 0
	s_lshl_b32 s4, s4, 10
	s_add_u32 s4, s4, 0x8000
	s_mov_b32 s5, 0
	s_add_i32 m0, s10, 0x2080
	v_lshl_add_u64 v[236:237], v[178:179], 0, s[4:5]
	global_load_lds_dwordx4 v[236:237], off
	s_xor_b32 s4, s11, 0
	s_lshl_b32 s4, s4, 10
	s_add_u32 s4, s4, 0x10000
	s_mov_b32 s5, 0
	s_add_i32 m0, s10, 0x4100
	v_lshl_add_u64 v[236:237], v[178:179], 0, s[4:5]
	global_load_lds_dwordx4 v[236:237], off
	s_xor_b32 s4, s11, 0
	s_lshl_b32 s4, s4, 10
	s_add_u32 s4, s4, 0x18000
	s_mov_b32 s5, 0
	s_add_i32 m0, s10, 0x6180
	v_lshl_add_u64 v[236:237], v[178:179], 0, s[4:5]
	global_load_lds_dwordx4 v[236:237], off
	global_load_dwordx4 v[0:3], v[240:241], off
	global_load_dwordx4 v[4:7], v[240:241], off offset:64
	global_load_dwordx4 v[8:11], v[240:241], off offset:128
	global_load_dwordx4 v[12:15], v[240:241], off offset:192
	global_load_dwordx4 v[16:19], v[240:241], off offset:256
	global_load_dwordx4 v[20:23], v[240:241], off offset:320
	global_load_dwordx4 v[24:27], v[240:241], off offset:384
	global_load_dwordx4 v[28:31], v[240:241], off offset:448
	global_load_dwordx4 v[32:35], v[240:241], off offset:512
	global_load_dwordx4 v[36:39], v[240:241], off offset:576
	global_load_dwordx4 v[40:43], v[240:241], off offset:640
	global_load_dwordx4 v[44:47], v[240:241], off offset:704
	global_load_dwordx4 v[48:51], v[240:241], off offset:768
	global_load_dwordx4 v[52:55], v[240:241], off offset:832
	global_load_dwordx4 v[56:59], v[240:241], off offset:896
	global_load_dwordx4 v[60:63], v[240:241], off offset:960
	s_xor_b32 s4, s11, 1
	s_lshl_b32 s4, s4, 10
	s_add_u32 s4, s4, 0x0
	s_mov_b32 s5, 0
	s_add_i32 m0, s10, 0x8200
	v_lshl_add_u64 v[236:237], v[178:179], 0, s[4:5]
	global_load_lds_dwordx4 v[236:237], off
	s_xor_b32 s4, s11, 1
	s_lshl_b32 s4, s4, 10
	s_add_u32 s4, s4, 0x8000
	s_mov_b32 s5, 0
	s_add_i32 m0, s10, 0xa280
	v_lshl_add_u64 v[236:237], v[178:179], 0, s[4:5]
	global_load_lds_dwordx4 v[236:237], off
	s_xor_b32 s4, s11, 1
	s_lshl_b32 s4, s4, 10
	s_add_u32 s4, s4, 0x10000
	s_mov_b32 s5, 0
	s_add_i32 m0, s10, 0xc300
	v_lshl_add_u64 v[236:237], v[178:179], 0, s[4:5]
	global_load_lds_dwordx4 v[236:237], off
	s_xor_b32 s4, s11, 1
	s_lshl_b32 s4, s4, 10
	s_add_u32 s4, s4, 0x18000
	s_mov_b32 s5, 0
	s_add_i32 m0, s10, 0xe380
	v_lshl_add_u64 v[236:237], v[178:179], 0, s[4:5]
	global_load_lds_dwordx4 v[236:237], off
	global_load_dwordx4 v[64:67], v[242:243], off
	global_load_dwordx4 v[68:71], v[242:243], off offset:64
	global_load_dwordx4 v[72:75], v[242:243], off offset:128
	global_load_dwordx4 v[76:79], v[242:243], off offset:192
	global_load_dwordx4 v[80:83], v[242:243], off offset:256
	global_load_dwordx4 v[84:87], v[242:243], off offset:320
	global_load_dwordx4 v[88:91], v[242:243], off offset:384
	global_load_dwordx4 v[92:95], v[242:243], off offset:448
	global_load_dwordx4 v[96:99], v[242:243], off offset:512
	global_load_dwordx4 v[100:103], v[242:243], off offset:576
	global_load_dwordx4 v[104:107], v[242:243], off offset:640
	global_load_dwordx4 v[108:111], v[242:243], off offset:704
	global_load_dwordx4 v[112:115], v[242:243], off offset:768
	global_load_dwordx4 v[116:119], v[242:243], off offset:832
	global_load_dwordx4 v[120:123], v[242:243], off offset:896
	global_load_dwordx4 v[124:127], v[242:243], off offset:960
	s_xor_b32 s4, s11, 2
	s_lshl_b32 s4, s4, 10
	s_add_u32 s4, s4, 0x0
	s_mov_b32 s5, 0
	s_add_i32 m0, s10, 0x10400
	v_lshl_add_u64 v[236:237], v[178:179], 0, s[4:5]
	global_load_lds_dwordx4 v[236:237], off
	s_xor_b32 s4, s11, 2
	s_lshl_b32 s4, s4, 10
	s_add_u32 s4, s4, 0x8000
	s_mov_b32 s5, 0
	s_add_i32 m0, s10, 0x12480
	v_lshl_add_u64 v[236:237], v[178:179], 0, s[4:5]
	global_load_lds_dwordx4 v[236:237], off
	s_xor_b32 s4, s11, 2
	s_lshl_b32 s4, s4, 10
	s_add_u32 s4, s4, 0x10000
	s_mov_b32 s5, 0
	s_add_i32 m0, s10, 0x14500
	v_lshl_add_u64 v[236:237], v[178:179], 0, s[4:5]
	global_load_lds_dwordx4 v[236:237], off
	s_xor_b32 s4, s11, 2
	s_lshl_b32 s4, s4, 10
	s_add_u32 s4, s4, 0x18000
	s_mov_b32 s5, 0
	s_add_i32 m0, s10, 0x16580
	v_lshl_add_u64 v[236:237], v[178:179], 0, s[4:5]
	global_load_lds_dwordx4 v[236:237], off
	global_load_dwordx4 v[128:131], v[248:249], off
	global_load_dwordx4 v[132:135], v[248:249], off offset:64
	global_load_dwordx4 v[136:139], v[248:249], off offset:128
	global_load_dwordx4 v[140:143], v[248:249], off offset:192
	global_load_dwordx4 v[144:147], v[248:249], off offset:256
	global_load_dwordx4 v[148:151], v[248:249], off offset:320
	global_load_dwordx4 v[204:207], v[248:249], off offset:384
	global_load_dwordx4 v[208:211], v[248:249], off offset:448
	global_load_dwordx4 v[212:215], v[248:249], off offset:512
	global_load_dwordx4 v[216:219], v[248:249], off offset:576
	global_load_dwordx4 v[220:223], v[248:249], off offset:640
	global_load_dwordx4 v[224:227], v[248:249], off offset:704
	s_waitcnt vmcnt(52)
	s_barrier
; #define SG_LA(c, d) do { _Pragma("unroll") for (int ks = 0; ks < 16; ++ks) d[ks] = *(const bf16x8*)(ap + (c) * CK + ks * 32); } while (0)
; #define SG_LB(c) do { _Pragma("unroll") for (int i = 0; i < 4; ++i) sb[i] = *(const u32x4*)(bp + (size_t)(8 * i) * DM + (c) * CK); } while (0)
; #define SG_SB(bufp) do { _Pragma("unroll") for (int i = 0; i < 4; ++i) *(LAS u32x4*)((bufp) + bw + (unsigned)(8 * i * BS * 2)) = sb[i]; } while (0)
; __device__ __forceinline__ void sample_gemm32(LAS unsigned char* lds, const bf16_t* A, const bf16_t* Bt, float* out, int ldo, int n0, int tid, int lane, int wave) {
;     ...
; #pragma unroll 1
;     for (int c = 0; c < NC; c += 2) {
;         SG_LA(c + 1, fn);
;         SG_MM(fa, c);
;         SG_SB(lds + ((c + 1) & 1) * BUFB);
;         if (c + 2 < NC) SG_LB(c + 2);
	ds_read_b128 v[180:183], v152 offset:0
	ds_read_b128 v[184:187], v152 offset:16640
	ds_read_b128 v[188:191], v152 offset:64
	ds_read_b128 v[244:247], v152 offset:16704
	s_waitcnt vmcnt(51)
	s_waitcnt lgkmcnt(2)
	v_mfma_f32_16x16x32_bf16 v[228:231], v[0:3], v[180:183], v[228:231]
	v_mfma_f32_16x16x32_bf16 v[232:235], v[0:3], v[184:187], v[232:235]
	global_load_dwordx4 v[0:3], v[248:249], off offset:768
	ds_read_b128 v[180:183], v152 offset:128
	ds_read_b128 v[184:187], v152 offset:16768
	s_waitcnt vmcnt(51)
	s_waitcnt lgkmcnt(2)
	v_mfma_f32_16x16x32_bf16 v[228:231], v[4:7], v[188:191], v[228:231]
	v_mfma_f32_16x16x32_bf16 v[232:235], v[4:7], v[244:247], v[232:235]
	global_load_dwordx4 v[4:7], v[248:249], off offset:832
	ds_read_b128 v[188:191], v152 offset:192
	ds_read_b128 v[244:247], v152 offset:16832
	s_waitcnt vmcnt(51)
	s_waitcnt lgkmcnt(2)
	v_mfma_f32_16x16x32_bf16 v[228:231], v[8:11], v[180:183], v[228:231]
	v_mfma_f32_16x16x32_bf16 v[232:235], v[8:11], v[184:187], v[232:235]
	global_load_dwordx4 v[8:11], v[248:249], off offset:896
	ds_read_b128 v[180:183], v152 offset:256
	ds_read_b128 v[184:187], v152 offset:16896
	s_waitcnt vmcnt(51)
	s_waitcnt lgkmcnt(2)
	v_mfma_f32_16x16x32_bf16 v[228:231], v[12:15], v[188:191], v[228:231]
	v_mfma_f32_16x16x32_bf16 v[232:235], v[12:15], v[244:247], v[232:235]
	global_load_dwordx4 v[12:15], v[248:249], off offset:960
	ds_read_b128 v[188:191], v152 offset:320
	ds_read_b128 v[244:247], v152 offset:16960
	s_waitcnt vmcnt(51)
	s_waitcnt lgkmcnt(2)
	v_mfma_f32_16x16x32_bf16 v[228:231], v[16:19], v[180:183], v[228:231]
	v_mfma_f32_16x16x32_bf16 v[232:235], v[16:19], v[184:187], v[232:235]
	global_load_dwordx4 v[16:19], v[250:251], off
	ds_read_b128 v[180:183], v152 offset:384
	ds_read_b128 v[184:187], v152 offset:17024
	s_waitcnt vmcnt(51)
	s_waitcnt lgkmcnt(2)
	v_mfma_f32_16x16x32_bf16 v[228:231], v[20:23], v[188:191], v[228:231]
	v_mfma_f32_16x16x32_bf16 v[232:235], v[20:23], v[244:247], v[232:235]
	global_load_dwordx4 v[20:23], v[250:251], off offset:64
	ds_read_b128 v[188:191], v152 offset:448
	ds_read_b128 v[244:247], v152 offset:17088
	s_waitcnt vmcnt(51)
	s_waitcnt lgkmcnt(2)
	v_mfma_f32_16x16x32_bf16 v[228:231], v[24:27], v[180:183], v[228:231]
	v_mfma_f32_16x16x32_bf16 v[232:235], v[24:27], v[184:187], v[232:235]
	global_load_dwordx4 v[24:27], v[250:251], off offset:128
	ds_read_b128 v[180:183], v152 offset:512
	ds_read_b128 v[184:187], v152 offset:17152
	s_waitcnt vmcnt(51)
	s_waitcnt lgkmcnt(2)
	v_mfma_f32_16x16x32_bf16 v[228:231], v[28:31], v[188:191], v[228:231]
	v_mfma_f32_16x16x32_bf16 v[232:235], v[28:31], v[244:247], v[232:235]
	global_load_dwordx4 v[28:31], v[250:251], off offset:192
	ds_read_b128 v[188:191], v152 offset:576
	ds_read_b128 v[244:247], v152 offset:17216
	s_waitcnt vmcnt(51)
	s_waitcnt lgkmcnt(2)
	v_mfma_f32_16x16x32_bf16 v[228:231], v[32:35], v[180:183], v[228:231]
	v_mfma_f32_16x16x32_bf16 v[232:235], v[32:35], v[184:187], v[232:235]
	global_load_dwordx4 v[32:35], v[250:251], off offset:256
	ds_read_b128 v[180:183], v152 offset:640
	ds_read_b128 v[184:187], v152 offset:17280
	s_waitcnt vmcnt(51)
	s_waitcnt lgkmcnt(2)
	v_mfma_f32_16x16x32_bf16 v[228:231], v[36:39], v[188:191], v[228:231]
	v_mfma_f32_16x16x32_bf16 v[232:235], v[36:39], v[244:247], v[232:235]
	global_load_dwordx4 v[36:39], v[250:251], off offset:320
	ds_read_b128 v[188:191], v152 offset:704
	ds_read_b128 v[244:247], v152 offset:17344
	s_waitcnt vmcnt(51)
	s_waitcnt lgkmcnt(2)
	v_mfma_f32_16x16x32_bf16 v[228:231], v[40:43], v[180:183], v[228:231]
	v_mfma_f32_16x16x32_bf16 v[232:235], v[40:43], v[184:187], v[232:235]
	global_load_dwordx4 v[40:43], v[250:251], off offset:384
	ds_read_b128 v[180:183], v152 offset:768
	ds_read_b128 v[184:187], v152 offset:17408
	s_waitcnt vmcnt(51)
	s_waitcnt lgkmcnt(2)
	v_mfma_f32_16x16x32_bf16 v[228:231], v[44:47], v[188:191], v[228:231]
	v_mfma_f32_16x16x32_bf16 v[232:235], v[44:47], v[244:247], v[232:235]
	global_load_dwordx4 v[44:47], v[250:251], off offset:448
	ds_read_b128 v[188:191], v152 offset:832
	ds_read_b128 v[244:247], v152 offset:17472
	s_waitcnt vmcnt(51)
	s_waitcnt lgkmcnt(2)
	v_mfma_f32_16x16x32_bf16 v[228:231], v[48:51], v[180:183], v[228:231]
	v_mfma_f32_16x16x32_bf16 v[232:235], v[48:51], v[184:187], v[232:235]
	global_load_dwordx4 v[48:51], v[250:251], off offset:512
	ds_read_b128 v[180:183], v152 offset:896
	ds_read_b128 v[184:187], v152 offset:17536
	s_waitcnt vmcnt(51)
	s_waitcnt lgkmcnt(2)
	v_mfma_f32_16x16x32_bf16 v[228:231], v[52:55], v[188:191], v[228:231]
	v_mfma_f32_16x16x32_bf16 v[232:235], v[52:55], v[244:247], v[232:235]
	global_load_dwordx4 v[52:55], v[250:251], off offset:576
	ds_read_b128 v[188:191], v152 offset:960
	ds_read_b128 v[244:247], v152 offset:17600
	s_waitcnt vmcnt(51)
	s_waitcnt lgkmcnt(2)
	v_mfma_f32_16x16x32_bf16 v[228:231], v[56:59], v[180:183], v[228:231]
	v_mfma_f32_16x16x32_bf16 v[232:235], v[56:59], v[184:187], v[232:235]
	global_load_dwordx4 v[56:59], v[250:251], off offset:640
	s_waitcnt vmcnt(51)
	s_waitcnt lgkmcnt(0)
	v_mfma_f32_16x16x32_bf16 v[228:231], v[60:63], v[188:191], v[228:231]
	v_mfma_f32_16x16x32_bf16 v[232:235], v[60:63], v[244:247], v[232:235]
	global_load_dwordx4 v[60:63], v[250:251], off offset:704
	s_waitcnt lgkmcnt(0)
	s_barrier
; #define LBAR() do { asm volatile("s_waitcnt lgkmcnt(0)" ::: "memory"); __builtin_amdgcn_s_barrier(); asm volatile("" ::: "memory"); } while (0)
; #define SG_LA(c, d) do { _Pragma("unroll") for (int ks = 0; ks < 16; ++ks) d[ks] = *(const bf16x8*)(ap + (c) * CK + ks * 32); } while (0)
; #define SG_LB(c) do { _Pragma("unroll") for (int i = 0; i < 4; ++i) sb[i] = *(const u32x4*)(bp + (size_t)(8 * i) * DM + (c) * CK); } while (0)
; #define SG_SB(bufp) do { _Pragma("unroll") for (int i = 0; i < 4; ++i) *(LAS u32x4*)((bufp) + bw + (unsigned)(8 * i * BS * 2)) = sb[i]; } while (0)
; __device__ __forceinline__ void sample_gemm32(LAS unsigned char* lds, const bf16_t* A, const bf16_t* Bt, float* out, int ldo, int n0, int tid, int lane, int wave) {
;     ...
; #pragma unroll 1
;     for (int c = 0; c < NC; c += 2) {
;         SG_LA(c + 1, fn);
;         SG_MM(fa, c);
;         SG_SB(lds + ((c + 1) & 1) * BUFB);
;         if (c + 2 < NC) SG_LB(c + 2);
;         LBAR();
;         if (c + 2 < NC) SG_LA(c + 2, fa);
;         SG_MM(fn, c + 1);
;         if (c + 2 < NC) SG_SB(lds + ((c + 2) & 1) * BUFB);
;         if (c + 3 < NC) SG_LB(c + 3);
;         LBAR();
	s_xor_b32 s4, s11, 3
	s_lshl_b32 s4, s4, 10
	s_add_u32 s4, s4, 0x0
	s_mov_b32 s5, 0
	s_add_i32 m0, s10, 0x0
	v_lshl_add_u64 v[236:237], v[178:179], 0, s[4:5]
	global_load_lds_dwordx4 v[236:237], off
	s_xor_b32 s4, s11, 3
	s_lshl_b32 s4, s4, 10
	s_add_u32 s4, s4, 0x8000
	s_mov_b32 s5, 0
	s_add_i32 m0, s10, 0x2080
	v_lshl_add_u64 v[236:237], v[178:179], 0, s[4:5]
	global_load_lds_dwordx4 v[236:237], off
	s_xor_b32 s4, s11, 3
	s_lshl_b32 s4, s4, 10
	s_add_u32 s4, s4, 0x10000
	s_mov_b32 s5, 0
	s_add_i32 m0, s10, 0x4100
	v_lshl_add_u64 v[236:237], v[178:179], 0, s[4:5]
	global_load_lds_dwordx4 v[236:237], off
	s_xor_b32 s4, s11, 3
	s_lshl_b32 s4, s4, 10
	s_add_u32 s4, s4, 0x18000
	s_mov_b32 s5, 0
	s_add_i32 m0, s10, 0x6180
	v_lshl_add_u64 v[236:237], v[178:179], 0, s[4:5]
	global_load_lds_dwordx4 v[236:237], off
	s_waitcnt vmcnt(52)
	s_barrier
	ds_read_b128 v[180:183], v152 offset:33280
	ds_read_b128 v[184:187], v152 offset:49920
	ds_read_b128 v[188:191], v152 offset:33344
	ds_read_b128 v[244:247], v152 offset:49984
	s_waitcnt vmcnt(51)
	s_waitcnt lgkmcnt(2)
	v_mfma_f32_16x16x32_bf16 v[228:231], v[64:67], v[180:183], v[228:231]
	v_mfma_f32_16x16x32_bf16 v[232:235], v[64:67], v[184:187], v[232:235]
	global_load_dwordx4 v[64:67], v[250:251], off offset:768
	ds_read_b128 v[180:183], v152 offset:33408
	ds_read_b128 v[184:187], v152 offset:50048
	s_waitcnt vmcnt(51)
	s_waitcnt lgkmcnt(2)
	v_mfma_f32_16x16x32_bf16 v[228:231], v[68:71], v[188:191], v[228:231]
	v_mfma_f32_16x16x32_bf16 v[232:235], v[68:71], v[244:247], v[232:235]
	global_load_dwordx4 v[68:71], v[250:251], off offset:832
	ds_read_b128 v[188:191], v152 offset:33472
	ds_read_b128 v[244:247], v152 offset:50112
	s_waitcnt vmcnt(51)
	s_waitcnt lgkmcnt(2)
	v_mfma_f32_16x16x32_bf16 v[228:231], v[72:75], v[180:183], v[228:231]
	v_mfma_f32_16x16x32_bf16 v[232:235], v[72:75], v[184:187], v[232:235]
	global_load_dwordx4 v[72:75], v[250:251], off offset:896
	ds_read_b128 v[180:183], v152 offset:33536
	ds_read_b128 v[184:187], v152 offset:50176
	s_waitcnt vmcnt(51)
	s_waitcnt lgkmcnt(2)
	v_mfma_f32_16x16x32_bf16 v[228:231], v[76:79], v[188:191], v[228:231]
	v_mfma_f32_16x16x32_bf16 v[232:235], v[76:79], v[244:247], v[232:235]
	global_load_dwordx4 v[76:79], v[250:251], off offset:960
	ds_read_b128 v[188:191], v152 offset:33600
	ds_read_b128 v[244:247], v152 offset:50240
	s_waitcnt vmcnt(51)
	s_waitcnt lgkmcnt(2)
	v_mfma_f32_16x16x32_bf16 v[228:231], v[80:83], v[180:183], v[228:231]
	v_mfma_f32_16x16x32_bf16 v[232:235], v[80:83], v[184:187], v[232:235]
	ds_read_b128 v[180:183], v152 offset:33664
	ds_read_b128 v[184:187], v152 offset:50304
	s_waitcnt vmcnt(50)
	s_waitcnt lgkmcnt(2)
	v_mfma_f32_16x16x32_bf16 v[228:231], v[84:87], v[188:191], v[228:231]
	v_mfma_f32_16x16x32_bf16 v[232:235], v[84:87], v[244:247], v[232:235]
	ds_read_b128 v[188:191], v152 offset:33728
	ds_read_b128 v[244:247], v152 offset:50368
	s_waitcnt vmcnt(49)
	s_waitcnt lgkmcnt(2)
	v_mfma_f32_16x16x32_bf16 v[228:231], v[88:91], v[180:183], v[228:231]
	v_mfma_f32_16x16x32_bf16 v[232:235], v[88:91], v[184:187], v[232:235]
	ds_read_b128 v[180:183], v152 offset:33792
	ds_read_b128 v[184:187], v152 offset:50432
	s_waitcnt vmcnt(48)
	s_waitcnt lgkmcnt(2)
	v_mfma_f32_16x16x32_bf16 v[228:231], v[92:95], v[188:191], v[228:231]
	v_mfma_f32_16x16x32_bf16 v[232:235], v[92:95], v[244:247], v[232:235]
	ds_read_b128 v[188:191], v152 offset:33856
	ds_read_b128 v[244:247], v152 offset:50496
	s_waitcnt vmcnt(47)
	s_waitcnt lgkmcnt(2)
	v_mfma_f32_16x16x32_bf16 v[228:231], v[96:99], v[180:183], v[228:231]
	v_mfma_f32_16x16x32_bf16 v[232:235], v[96:99], v[184:187], v[232:235]
	ds_read_b128 v[180:183], v152 offset:33920
	ds_read_b128 v[184:187], v152 offset:50560
	s_waitcnt vmcnt(46)
	s_waitcnt lgkmcnt(2)
	v_mfma_f32_16x16x32_bf16 v[228:231], v[100:103], v[188:191], v[228:231]
	v_mfma_f32_16x16x32_bf16 v[232:235], v[100:103], v[244:247], v[232:235]
	ds_read_b128 v[188:191], v152 offset:33984
	ds_read_b128 v[244:247], v152 offset:50624
	s_waitcnt vmcnt(45)
	s_waitcnt lgkmcnt(2)
	v_mfma_f32_16x16x32_bf16 v[228:231], v[104:107], v[180:183], v[228:231]
	v_mfma_f32_16x16x32_bf16 v[232:235], v[104:107], v[184:187], v[232:235]
	ds_read_b128 v[180:183], v152 offset:34048
	ds_read_b128 v[184:187], v152 offset:50688
	s_waitcnt vmcnt(44)
	s_waitcnt lgkmcnt(2)
	v_mfma_f32_16x16x32_bf16 v[228:231], v[108:111], v[188:191], v[228:231]
	v_mfma_f32_16x16x32_bf16 v[232:235], v[108:111], v[244:247], v[232:235]
	ds_read_b128 v[188:191], v152 offset:34112
	ds_read_b128 v[244:247], v152 offset:50752
	s_waitcnt vmcnt(43)
	s_waitcnt lgkmcnt(2)
	v_mfma_f32_16x16x32_bf16 v[228:231], v[112:115], v[180:183], v[228:231]
	v_mfma_f32_16x16x32_bf16 v[232:235], v[112:115], v[184:187], v[232:235]
	ds_read_b128 v[180:183], v152 offset:34176
	ds_read_b128 v[184:187], v152 offset:50816
	s_waitcnt vmcnt(42)
	s_waitcnt lgkmcnt(2)
	v_mfma_f32_16x16x32_bf16 v[228:231], v[116:119], v[188:191], v[228:231]
	v_mfma_f32_16x16x32_bf16 v[232:235], v[116:119], v[244:247], v[232:235]
	ds_read_b128 v[188:191], v152 offset:34240
	ds_read_b128 v[244:247], v152 offset:50880
	s_waitcnt vmcnt(41)
	s_waitcnt lgkmcnt(2)
	v_mfma_f32_16x16x32_bf16 v[228:231], v[120:123], v[180:183], v[228:231]
	v_mfma_f32_16x16x32_bf16 v[232:235], v[120:123], v[184:187], v[232:235]
	s_waitcnt vmcnt(40)
	s_waitcnt lgkmcnt(0)
	v_mfma_f32_16x16x32_bf16 v[228:231], v[124:127], v[188:191], v[228:231]
	v_mfma_f32_16x16x32_bf16 v[232:235], v[124:127], v[244:247], v[232:235]
	s_waitcnt vmcnt(36)
	s_barrier
; #define LBAR() do { asm volatile("s_waitcnt lgkmcnt(0)" ::: "memory"); __builtin_amdgcn_s_barrier(); asm volatile("" ::: "memory"); } while (0)
; #define SG_LA(c, d) do { _Pragma("unroll") for (int ks = 0; ks < 16; ++ks) d[ks] = *(const bf16x8*)(ap + (c) * CK + ks * 32); } while (0)
; #define SG_LB(c) do { _Pragma("unroll") for (int i = 0; i < 4; ++i) sb[i] = *(const u32x4*)(bp + (size_t)(8 * i) * DM + (c) * CK); } while (0)
; #define SG_SB(bufp) do { _Pragma("unroll") for (int i = 0; i < 4; ++i) *(LAS u32x4*)((bufp) + bw + (unsigned)(8 * i * BS * 2)) = sb[i]; } while (0)
; __device__ __forceinline__ void sample_gemm32(LAS unsigned char* lds, const bf16_t* A, const bf16_t* Bt, float* out, int ldo, int n0, int tid, int lane, int wave) {
;     ...
; #pragma unroll 1
;     for (int c = 0; c < NC; c += 2) {
;         SG_LA(c + 1, fn);
;         SG_MM(fa, c);
;         SG_SB(lds + ((c + 1) & 1) * BUFB);
;         if (c + 2 < NC) SG_LB(c + 2);
;         LBAR();
;         if (c + 2 < NC) SG_LA(c + 2, fa);
;         SG_MM(fn, c + 1);
;         if (c + 2 < NC) SG_SB(lds + ((c + 2) & 1) * BUFB);
;         if (c + 3 < NC) SG_LB(c + 3);
;         LBAR();
	ds_read_b128 v[180:183], v238 offset:0
	ds_read_b128 v[184:187], v238 offset:16640
	ds_read_b128 v[188:191], v238 offset:64
	ds_read_b128 v[244:247], v238 offset:16704
	s_waitcnt vmcnt(35)
	s_waitcnt lgkmcnt(2)
	v_mfma_f32_16x16x32_bf16 v[228:231], v[128:131], v[180:183], v[228:231]
	v_mfma_f32_16x16x32_bf16 v[232:235], v[128:131], v[184:187], v[232:235]
	ds_read_b128 v[180:183], v238 offset:128
	ds_read_b128 v[184:187], v238 offset:16768
	s_waitcnt vmcnt(34)
	s_waitcnt lgkmcnt(2)
	v_mfma_f32_16x16x32_bf16 v[228:231], v[132:135], v[188:191], v[228:231]
	v_mfma_f32_16x16x32_bf16 v[232:235], v[132:135], v[244:247], v[232:235]
	ds_read_b128 v[188:191], v238 offset:192
	ds_read_b128 v[244:247], v238 offset:16832
	s_waitcnt vmcnt(33)
	s_waitcnt lgkmcnt(2)
	v_mfma_f32_16x16x32_bf16 v[228:231], v[136:139], v[180:183], v[228:231]
	v_mfma_f32_16x16x32_bf16 v[232:235], v[136:139], v[184:187], v[232:235]
	ds_read_b128 v[180:183], v238 offset:256
	ds_read_b128 v[184:187], v238 offset:16896
	s_waitcnt vmcnt(32)
	s_waitcnt lgkmcnt(2)
	v_mfma_f32_16x16x32_bf16 v[228:231], v[140:143], v[188:191], v[228:231]
	v_mfma_f32_16x16x32_bf16 v[232:235], v[140:143], v[244:247], v[232:235]
	ds_read_b128 v[188:191], v238 offset:320
	ds_read_b128 v[244:247], v238 offset:16960
	s_waitcnt vmcnt(31)
	s_waitcnt lgkmcnt(2)
	v_mfma_f32_16x16x32_bf16 v[228:231], v[144:147], v[180:183], v[228:231]
	v_mfma_f32_16x16x32_bf16 v[232:235], v[144:147], v[184:187], v[232:235]
	ds_read_b128 v[180:183], v238 offset:384
	ds_read_b128 v[184:187], v238 offset:17024
	s_waitcnt vmcnt(30)
	s_waitcnt lgkmcnt(2)
	v_mfma_f32_16x16x32_bf16 v[228:231], v[148:151], v[188:191], v[228:231]
	v_mfma_f32_16x16x32_bf16 v[232:235], v[148:151], v[244:247], v[232:235]
	ds_read_b128 v[188:191], v238 offset:448
	ds_read_b128 v[244:247], v238 offset:17088
	s_waitcnt vmcnt(29)
	s_waitcnt lgkmcnt(2)
	v_mfma_f32_16x16x32_bf16 v[228:231], v[204:207], v[180:183], v[228:231]
	v_mfma_f32_16x16x32_bf16 v[232:235], v[204:207], v[184:187], v[232:235]
	ds_read_b128 v[180:183], v238 offset:512
	ds_read_b128 v[184:187], v238 offset:17152
	s_waitcnt vmcnt(28)
	s_waitcnt lgkmcnt(2)
	v_mfma_f32_16x16x32_bf16 v[228:231], v[208:211], v[188:191], v[228:231]
	v_mfma_f32_16x16x32_bf16 v[232:235], v[208:211], v[244:247], v[232:235]
	ds_read_b128 v[188:191], v238 offset:576
	ds_read_b128 v[244:247], v238 offset:17216
	s_waitcnt vmcnt(27)
	s_waitcnt lgkmcnt(2)
	v_mfma_f32_16x16x32_bf16 v[228:231], v[212:215], v[180:183], v[228:231]
	v_mfma_f32_16x16x32_bf16 v[232:235], v[212:215], v[184:187], v[232:235]
	ds_read_b128 v[180:183], v238 offset:640
	ds_read_b128 v[184:187], v238 offset:17280
	s_waitcnt vmcnt(26)
	s_waitcnt lgkmcnt(2)
	v_mfma_f32_16x16x32_bf16 v[228:231], v[216:219], v[188:191], v[228:231]
	v_mfma_f32_16x16x32_bf16 v[232:235], v[216:219], v[244:247], v[232:235]
	ds_read_b128 v[188:191], v238 offset:704
	ds_read_b128 v[244:247], v238 offset:17344
	s_waitcnt vmcnt(25)
	s_waitcnt lgkmcnt(2)
	v_mfma_f32_16x16x32_bf16 v[228:231], v[220:223], v[180:183], v[228:231]
	v_mfma_f32_16x16x32_bf16 v[232:235], v[220:223], v[184:187], v[232:235]
	ds_read_b128 v[180:183], v238 offset:768
	ds_read_b128 v[184:187], v238 offset:17408
	s_waitcnt vmcnt(24)
	s_waitcnt lgkmcnt(2)
	v_mfma_f32_16x16x32_bf16 v[228:231], v[224:227], v[188:191], v[228:231]
	v_mfma_f32_16x16x32_bf16 v[232:235], v[224:227], v[244:247], v[232:235]
	ds_read_b128 v[188:191], v238 offset:832
	ds_read_b128 v[244:247], v238 offset:17472
	s_waitcnt vmcnt(23)
	s_waitcnt lgkmcnt(2)
	v_mfma_f32_16x16x32_bf16 v[228:231], v[0:3], v[180:183], v[228:231]
	v_mfma_f32_16x16x32_bf16 v[232:235], v[0:3], v[184:187], v[232:235]
	ds_read_b128 v[180:183], v238 offset:896
	ds_read_b128 v[184:187], v238 offset:17536
	s_waitcnt vmcnt(22)
	s_waitcnt lgkmcnt(2)
	v_mfma_f32_16x16x32_bf16 v[228:231], v[4:7], v[188:191], v[228:231]
	v_mfma_f32_16x16x32_bf16 v[232:235], v[4:7], v[244:247], v[232:235]
	ds_read_b128 v[188:191], v238 offset:960
	ds_read_b128 v[244:247], v238 offset:17600
	s_waitcnt vmcnt(21)
	s_waitcnt lgkmcnt(2)
	v_mfma_f32_16x16x32_bf16 v[228:231], v[8:11], v[180:183], v[228:231]
	v_mfma_f32_16x16x32_bf16 v[232:235], v[8:11], v[184:187], v[232:235]
	s_waitcnt vmcnt(20)
	s_waitcnt lgkmcnt(0)
	v_mfma_f32_16x16x32_bf16 v[228:231], v[12:15], v[188:191], v[228:231]
	v_mfma_f32_16x16x32_bf16 v[232:235], v[12:15], v[244:247], v[232:235]
	s_waitcnt vmcnt(4)
	s_barrier
; #define LBAR() do { asm volatile("s_waitcnt lgkmcnt(0)" ::: "memory"); __builtin_amdgcn_s_barrier(); asm volatile("" ::: "memory"); } while (0)
; #define SG_LA(c, d) do { _Pragma("unroll") for (int ks = 0; ks < 16; ++ks) d[ks] = *(const bf16x8*)(ap + (c) * CK + ks * 32); } while (0)
; #define SG_LB(c) do { _Pragma("unroll") for (int i = 0; i < 4; ++i) sb[i] = *(const u32x4*)(bp + (size_t)(8 * i) * DM + (c) * CK); } while (0)
; #define SG_SB(bufp) do { _Pragma("unroll") for (int i = 0; i < 4; ++i) *(LAS u32x4*)((bufp) + bw + (unsigned)(8 * i * BS * 2)) = sb[i]; } while (0)
; __device__ __forceinline__ void sample_gemm32(LAS unsigned char* lds, const bf16_t* A, const bf16_t* Bt, float* out, int ldo, int n0, int tid, int lane, int wave) {
;     ...
; #pragma unroll 1
;     for (int c = 0; c < NC; c += 2) {
;         SG_LA(c + 1, fn);
;         SG_MM(fa, c);
;         SG_SB(lds + ((c + 1) & 1) * BUFB);
;         if (c + 2 < NC) SG_LB(c + 2);
;         LBAR();
;         if (c + 2 < NC) SG_LA(c + 2, fa);
;         SG_MM(fn, c + 1);
;         if (c + 2 < NC) SG_SB(lds + ((c + 2) & 1) * BUFB);
;         if (c + 3 < NC) SG_LB(c + 3);
;         LBAR();
;     }
;     ...
; #pragma unroll
;     for (int nt = 0; nt < 2; ++nt)
; #pragma unroll
;         for (int j = 0; j < 4; ++j) out[(size_t)(wave * 16 + q8 * 4 + j) * ldo + n0 + nt * 16 + r] = acc[nt][j];
	ds_read_b128 v[180:183], v152 offset:0
	ds_read_b128 v[184:187], v152 offset:16640
	ds_read_b128 v[188:191], v152 offset:64
	ds_read_b128 v[244:247], v152 offset:16704
	s_waitcnt vmcnt(19)
	s_waitcnt lgkmcnt(2)
	v_mfma_f32_16x16x32_bf16 v[228:231], v[16:19], v[180:183], v[228:231]
	v_mfma_f32_16x16x32_bf16 v[232:235], v[16:19], v[184:187], v[232:235]
	ds_read_b128 v[180:183], v152 offset:128
	ds_read_b128 v[184:187], v152 offset:16768
	s_waitcnt vmcnt(18)
	s_waitcnt lgkmcnt(2)
	v_mfma_f32_16x16x32_bf16 v[228:231], v[20:23], v[188:191], v[228:231]
	v_mfma_f32_16x16x32_bf16 v[232:235], v[20:23], v[244:247], v[232:235]
	ds_read_b128 v[188:191], v152 offset:192
	ds_read_b128 v[244:247], v152 offset:16832
	s_waitcnt vmcnt(17)
	s_waitcnt lgkmcnt(2)
	v_mfma_f32_16x16x32_bf16 v[228:231], v[24:27], v[180:183], v[228:231]
	v_mfma_f32_16x16x32_bf16 v[232:235], v[24:27], v[184:187], v[232:235]
	ds_read_b128 v[180:183], v152 offset:256
	ds_read_b128 v[184:187], v152 offset:16896
	s_waitcnt vmcnt(16)
	s_waitcnt lgkmcnt(2)
	v_mfma_f32_16x16x32_bf16 v[228:231], v[28:31], v[188:191], v[228:231]
	v_mfma_f32_16x16x32_bf16 v[232:235], v[28:31], v[244:247], v[232:235]
	ds_read_b128 v[188:191], v152 offset:320
	ds_read_b128 v[244:247], v152 offset:16960
	s_waitcnt vmcnt(15)
	s_waitcnt lgkmcnt(2)
	v_mfma_f32_16x16x32_bf16 v[228:231], v[32:35], v[180:183], v[228:231]
	v_mfma_f32_16x16x32_bf16 v[232:235], v[32:35], v[184:187], v[232:235]
	ds_read_b128 v[180:183], v152 offset:384
	ds_read_b128 v[184:187], v152 offset:17024
	s_waitcnt vmcnt(14)
	s_waitcnt lgkmcnt(2)
	v_mfma_f32_16x16x32_bf16 v[228:231], v[36:39], v[188:191], v[228:231]
	v_mfma_f32_16x16x32_bf16 v[232:235], v[36:39], v[244:247], v[232:235]
	ds_read_b128 v[188:191], v152 offset:448
	ds_read_b128 v[244:247], v152 offset:17088
	s_waitcnt vmcnt(13)
	s_waitcnt lgkmcnt(2)
	v_mfma_f32_16x16x32_bf16 v[228:231], v[40:43], v[180:183], v[228:231]
	v_mfma_f32_16x16x32_bf16 v[232:235], v[40:43], v[184:187], v[232:235]
	ds_read_b128 v[180:183], v152 offset:512
	ds_read_b128 v[184:187], v152 offset:17152
	s_waitcnt vmcnt(12)
	s_waitcnt lgkmcnt(2)
	v_mfma_f32_16x16x32_bf16 v[228:231], v[44:47], v[188:191], v[228:231]
	v_mfma_f32_16x16x32_bf16 v[232:235], v[44:47], v[244:247], v[232:235]
	ds_read_b128 v[188:191], v152 offset:576
	ds_read_b128 v[244:247], v152 offset:17216
	s_waitcnt vmcnt(11)
	s_waitcnt lgkmcnt(2)
	v_mfma_f32_16x16x32_bf16 v[228:231], v[48:51], v[180:183], v[228:231]
	v_mfma_f32_16x16x32_bf16 v[232:235], v[48:51], v[184:187], v[232:235]
	ds_read_b128 v[180:183], v152 offset:640
	ds_read_b128 v[184:187], v152 offset:17280
	s_waitcnt vmcnt(10)
	s_waitcnt lgkmcnt(2)
	v_mfma_f32_16x16x32_bf16 v[228:231], v[52:55], v[188:191], v[228:231]
	v_mfma_f32_16x16x32_bf16 v[232:235], v[52:55], v[244:247], v[232:235]
	ds_read_b128 v[188:191], v152 offset:704
	ds_read_b128 v[244:247], v152 offset:17344
	s_waitcnt vmcnt(9)
	s_waitcnt lgkmcnt(2)
	v_mfma_f32_16x16x32_bf16 v[228:231], v[56:59], v[180:183], v[228:231]
	v_mfma_f32_16x16x32_bf16 v[232:235], v[56:59], v[184:187], v[232:235]
	ds_read_b128 v[180:183], v152 offset:768
	ds_read_b128 v[184:187], v152 offset:17408
	s_waitcnt vmcnt(8)
	s_waitcnt lgkmcnt(2)
	v_mfma_f32_16x16x32_bf16 v[228:231], v[60:63], v[188:191], v[228:231]
	v_mfma_f32_16x16x32_bf16 v[232:235], v[60:63], v[244:247], v[232:235]
	ds_read_b128 v[188:191], v152 offset:832
	ds_read_b128 v[244:247], v152 offset:17472
	s_waitcnt vmcnt(3)
	s_waitcnt lgkmcnt(2)
	v_mfma_f32_16x16x32_bf16 v[228:231], v[64:67], v[180:183], v[228:231]
	v_mfma_f32_16x16x32_bf16 v[232:235], v[64:67], v[184:187], v[232:235]
	ds_read_b128 v[180:183], v152 offset:896
	ds_read_b128 v[184:187], v152 offset:17536
	s_waitcnt vmcnt(2)
	s_waitcnt lgkmcnt(2)
	v_mfma_f32_16x16x32_bf16 v[228:231], v[68:71], v[188:191], v[228:231]
	v_mfma_f32_16x16x32_bf16 v[232:235], v[68:71], v[244:247], v[232:235]
	ds_read_b128 v[188:191], v152 offset:960
	ds_read_b128 v[244:247], v152 offset:17600
	s_waitcnt vmcnt(1)
	s_waitcnt lgkmcnt(2)
	v_mfma_f32_16x16x32_bf16 v[228:231], v[72:75], v[180:183], v[228:231]
	v_mfma_f32_16x16x32_bf16 v[232:235], v[72:75], v[184:187], v[232:235]
	s_waitcnt vmcnt(0)
	s_waitcnt lgkmcnt(0)
	v_mfma_f32_16x16x32_bf16 v[228:231], v[76:79], v[188:191], v[228:231]
	v_mfma_f32_16x16x32_bf16 v[232:235], v[76:79], v[244:247], v[232:235]
	s_nop 7
	v_mov_b32_e32 v84, v228
	v_mov_b32_e32 v85, v229
	v_mov_b32_e32 v86, v230
	v_mov_b32_e32 v87, v231
	v_mov_b32_e32 v80, v232
	v_mov_b32_e32 v81, v233
	v_mov_b32_e32 v82, v234
	v_mov_b32_e32 v83, v235
	s_branch .LBB0_349
